# v99 stack + P0 rmsnorm row loop: the 64-lane all-reduce of the row sum of squares via DPP (xor 1,2,4,8) and v_permlane16/32_swap instead of six ds_bpermute round trips
# speedup vs baseline: 1.0011x; 1.0011x over previous
; __global__ void __launch_bounds__(NWAVES * 64, 2) mk_fwd(Args args) {
;     ...
;                 float s = 0.f;
; #pragma unroll
;                 for (int j = 0; j < 4; ++j) s += (cur[j][0] * cur[j][0] + cur[j][1] * cur[j][1]) + (cur[j][2] * cur[j][2] + cur[j][3] * cur[j][3]);
;                 float z[8];
; #pragma unroll
;                 for (int h = 0; h < 8; ++h) z[h] = 0.f;
; #pragma unroll
;                 for (int j = 0; j < 4; ++j) { cur[j] = cur[j] * gg[j];
; #pragma unroll
;                     for (int h = 0; h < 8; ++h) z[h] += (cur[j][0] * wfr[h][j][0] + cur[j][1] * wfr[h][j][1]) + (cur[j][2] * wfr[h][j][2] + cur[j][3] * wfr[h][j][3]); }
;                 const float rs = 1.0f / sqrtf(wave_sum(s) * (1.f / DM) + EPS);
.LBB0_39:
	s_waitcnt lgkmcnt(0)
	v_pk_mul_f32 v[188:189], v[170:171], v[170:171]
	v_pk_mul_f32 v[200:201], v[168:169], v[168:169]
	v_mul_f32_e32 v187, v160, v160
	v_pk_mov_b32 v[202:203], v[200:201], v[188:189] op_sel:[1,0]
	v_mov_b32_e32 v201, v189
	v_pk_add_f32 v[188:189], v[202:203], v[200:201]
	v_pk_mul_f32 v[200:201], v[174:175], v[174:175]
	v_pk_mul_f32 v[202:203], v[172:173], v[172:173]
	v_mul_f32_e32 v199, v161, v161
	v_pk_mov_b32 v[204:205], v[202:203], v[200:201] op_sel:[1,0]
	v_mov_b32_e32 v203, v201
	v_pk_add_f32 v[200:201], v[204:205], v[202:203]
	v_pk_add_f32 v[188:189], v[188:189], v[188:189] op_sel:[0,1] op_sel_hi:[1,0]
	v_pk_add_f32 v[200:201], v[200:201], v[200:201] op_sel:[0,1] op_sel_hi:[1,0]
	v_pk_mul_f32 v[174:175], v[174:175], v[14:15]
	v_pk_mul_f32 v[172:173], v[172:173], v[12:13]
	v_mov_b32_e32 v201, v187
	v_mov_b32_e32 v189, v199
	v_mul_f32_e32 v187, v173, v141
	v_mul_f32_e32 v199, v175, v143
	v_fmac_f32_e32 v187, v172, v140
	v_fmac_f32_e32 v199, v174, v142
	v_mul_f32_e32 v202, v165, v165
	v_mul_f32_e32 v204, v167, v167
	v_pk_add_f32 v[188:189], v[200:201], v[188:189]
	v_add_f32_e32 v187, v187, v199
	v_mul_f32_e32 v199, v173, v125
	v_mul_f32_e32 v200, v175, v127
	v_mul_f32_e32 v206, v162, v162
	v_mul_f32_e32 v207, v163, v163
	v_pk_fma_f32 v[202:203], v[164:165], v[164:165], v[202:203] op_sel_hi:[1,1,0]
	v_pk_fma_f32 v[204:205], v[166:167], v[166:167], v[204:205] op_sel_hi:[1,1,0]
	v_fmac_f32_e32 v199, v172, v124
	v_fmac_f32_e32 v200, v174, v126
	v_mov_b32_e32 v203, v206
	v_mov_b32_e32 v205, v207
	v_add_f32_e32 v199, v199, v200
	v_mul_f32_e32 v200, v173, v109
	v_mul_f32_e32 v201, v175, v111
	v_pk_add_f32 v[202:203], v[202:203], v[204:205]
	v_fmac_f32_e32 v200, v172, v108
	v_fmac_f32_e32 v201, v174, v110
	v_pk_add_f32 v[188:189], v[188:189], v[202:203]
	v_add_f32_e32 v200, v200, v201
	v_mul_f32_e32 v201, v173, v93
	v_mul_f32_e32 v202, v175, v95
	v_fmac_f32_e32 v201, v172, v92
	v_fmac_f32_e32 v202, v174, v94
	v_add_f32_e32 v201, v201, v202
	v_mul_f32_e32 v202, v173, v77
	v_mul_f32_e32 v203, v175, v79
	v_fmac_f32_e32 v202, v172, v76
	v_fmac_f32_e32 v203, v174, v78
	v_add_f32_e32 v202, v202, v203
	v_mul_f32_e32 v203, v173, v61
	v_mul_f32_e32 v204, v175, v63
	v_fmac_f32_e32 v203, v172, v60
	v_fmac_f32_e32 v204, v174, v62
	v_add_f32_e32 v203, v203, v204
	v_mul_f32_e32 v204, v173, v45
	v_mul_f32_e32 v205, v175, v47
	v_fmac_f32_e32 v204, v172, v44
	v_fmac_f32_e32 v205, v174, v46
	v_add_f32_e32 v204, v204, v205
	v_mul_f32_e32 v205, v173, v29
	v_mul_f32_e32 v206, v175, v31
	v_fmac_f32_e32 v205, v172, v28
	v_fmac_f32_e32 v206, v174, v30
	v_pk_mul_f32 v[170:171], v[170:171], v[10:11]
	v_pk_mul_f32 v[168:169], v[168:169], v[8:9]
	v_add_f32_e32 v205, v205, v206
	v_mul_f32_e32 v206, v169, v137
	v_mul_f32_e32 v207, v171, v139
	v_fmac_f32_e32 v206, v168, v136
	v_fmac_f32_e32 v207, v170, v138
	v_add_f32_e32 v187, 0, v187
	v_add_f32_e32 v206, v206, v207
	v_add_f32_e32 v187, v187, v206
	v_mul_f32_e32 v206, v169, v121
	v_mul_f32_e32 v207, v171, v123
	v_fmac_f32_e32 v206, v168, v120
	v_fmac_f32_e32 v207, v170, v122
	v_add_f32_e32 v199, 0, v199
	v_add_f32_e32 v206, v206, v207
	v_add_f32_e32 v199, v199, v206
	v_mul_f32_e32 v206, v169, v105
	v_mul_f32_e32 v207, v171, v107
	v_fmac_f32_e32 v206, v168, v104
	v_fmac_f32_e32 v207, v170, v106
	v_add_f32_e32 v200, 0, v200
	v_add_f32_e32 v206, v206, v207
	v_add_f32_e32 v200, v200, v206
	v_mul_f32_e32 v206, v169, v89
	v_mul_f32_e32 v207, v171, v91
	v_fmac_f32_e32 v206, v168, v88
	v_fmac_f32_e32 v207, v170, v90
	v_add_f32_e32 v201, 0, v201
	v_add_f32_e32 v206, v206, v207
	v_add_f32_e32 v201, v201, v206
	v_mul_f32_e32 v206, v169, v73
	v_mul_f32_e32 v207, v171, v75
	v_fmac_f32_e32 v206, v168, v72
	v_fmac_f32_e32 v207, v170, v74
	v_add_f32_e32 v202, 0, v202
	v_add_f32_e32 v206, v206, v207
	v_add_f32_e32 v202, v202, v206
	v_mul_f32_e32 v206, v169, v57
	v_mul_f32_e32 v207, v171, v59
	v_fmac_f32_e32 v206, v168, v56
	v_fmac_f32_e32 v207, v170, v58
	v_add_f32_e32 v203, 0, v203
	v_add_f32_e32 v206, v206, v207
	v_add_f32_e32 v203, v203, v206
	v_mul_f32_e32 v206, v169, v41
	v_mul_f32_e32 v207, v171, v43
	v_fmac_f32_e32 v206, v168, v40
	v_fmac_f32_e32 v207, v170, v42
	v_add_f32_e32 v204, 0, v204
	v_add_f32_e32 v206, v206, v207
	v_add_f32_e32 v204, v204, v206
	v_mul_f32_e32 v206, v169, v25
	v_mul_f32_e32 v207, v171, v27
	v_fmac_f32_e32 v206, v168, v24
	v_fmac_f32_e32 v207, v170, v26
	v_add_f32_e32 v205, 0, v205
	v_add_f32_e32 v206, v206, v207
	v_pk_mul_f32 v[166:167], v[166:167], v[6:7]
	v_pk_mul_f32 v[164:165], v[164:165], v[4:5]
	v_add_f32_e32 v205, v205, v206
	v_mul_f32_e32 v206, v165, v133
	v_mul_f32_e32 v207, v167, v135
	v_fmac_f32_e32 v206, v164, v132
	v_fmac_f32_e32 v207, v166, v134
	v_add_f32_e32 v206, v206, v207
	v_add_f32_e32 v187, v187, v206
	v_mul_f32_e32 v206, v165, v117
	v_mul_f32_e32 v207, v167, v119
	v_fmac_f32_e32 v206, v164, v116
	v_fmac_f32_e32 v207, v166, v118
	v_add_f32_e32 v206, v206, v207
	v_add_f32_e32 v199, v199, v206
	v_mul_f32_e32 v206, v165, v101
	v_mul_f32_e32 v207, v167, v103
	v_fmac_f32_e32 v206, v164, v100
	v_fmac_f32_e32 v207, v166, v102
	v_add_f32_e32 v206, v206, v207
	v_add_f32_e32 v206, v200, v206
	v_mul_f32_e32 v200, v165, v85
	v_mul_f32_e32 v207, v167, v87
	v_fmac_f32_e32 v200, v164, v84
	v_fmac_f32_e32 v207, v166, v86
	v_add_f32_e32 v200, v200, v207
	v_add_f32_e32 v207, v201, v200
	v_mul_f32_e32 v200, v165, v69
	v_mul_f32_e32 v201, v167, v71
	v_fmac_f32_e32 v200, v164, v68
	v_fmac_f32_e32 v201, v166, v70
	v_add_f32_e32 v200, v200, v201
	v_add_f32_e32 v202, v202, v200
	v_mul_f32_e32 v200, v165, v53
	v_mul_f32_e32 v201, v167, v55
	v_fmac_f32_e32 v200, v164, v52
	v_fmac_f32_e32 v201, v166, v54
	v_add_f32_e32 v200, v200, v201
	v_add_f32_e32 v203, v203, v200
	v_mul_f32_e32 v200, v165, v37
	v_mul_f32_e32 v201, v167, v39
	v_fmac_f32_e32 v200, v164, v36
	v_fmac_f32_e32 v201, v166, v38
	v_add_f32_e32 v200, v200, v201
	v_add_f32_e32 v204, v204, v200
	v_mul_f32_e32 v200, v165, v21
	v_mul_f32_e32 v201, v167, v23
	v_fmac_f32_e32 v200, v164, v20
	v_fmac_f32_e32 v201, v166, v22
	v_add_f32_e32 v200, v200, v201
	v_add_f32_e32 v205, v205, v200
	v_pk_mul_f32 v[162:163], v[162:163], v[2:3]
	v_pk_mul_f32 v[200:201], v[160:161], v[0:1]
	v_mul_f32_e32 v161, v163, v131
	v_mul_f32_e32 v160, v201, v129
	v_fmac_f32_e32 v160, v200, v128
	v_fmac_f32_e32 v161, v162, v130
	v_add_f32_e32 v160, v160, v161
	v_add_f32_e32 v161, v187, v160
	v_mul_f32_e32 v160, v201, v113
	v_mul_f32_e32 v187, v163, v115
	v_fmac_f32_e32 v160, v200, v112
	v_fmac_f32_e32 v187, v162, v114
	v_add_f32_e32 v160, v160, v187
	v_add_f32_e32 v187, v199, v160
	v_mul_f32_e32 v160, v201, v97
	v_mul_f32_e32 v199, v163, v99
	v_fmac_f32_e32 v160, v200, v96
	v_fmac_f32_e32 v199, v162, v98
	v_add_f32_e32 v160, v160, v199
	v_add_f32_e32 v199, v206, v160
	v_add_f32_e32 v160, v188, v189
	v_mul_f32_e32 v189, v201, v81
	v_mul_f32_e32 v206, v163, v83
	v_fmac_f32_e32 v189, v200, v80
	v_fmac_f32_e32 v206, v162, v82
	s_waitcnt lgkmcnt(0)
; __device__ __forceinline__ unsigned pk2(float lo, float hi) { return pg8::cvt_pk_bf16(lo, hi); }
; __global__ void __launch_bounds__(NWAVES * 64, 2) mk_fwd(Args args) {
;     ...
;                 const float rs = 1.0f / sqrtf(wave_sum(s) * (1.f / DM) + EPS);
;                 unsigned long long* o8 = (unsigned long long*)(XN + (size_t)m * DM) + lane;
; #pragma unroll
;                 for (int j = 0; j < 4; ++j) { const f32x4 v = cur[j] * rs; o8[64 * j] = (unsigned long long)pk2(v[0], v[1]) | ((unsigned long long)pk2(v[2], v[3]) << 32); }
;                 float s4[4], s2[2], s1;
; #pragma unroll
;                 for (int i = 0; i < 4; ++i) { const float send = (lane & 32) ? z[i] : z[4 + i], keep = (lane & 32) ? z[4 + i] : z[i]; s4[i] = keep + __shfl_xor(send, 32); }
; #pragma unroll
;                 for (int i = 0; i < 2; ++i) { const float send = (lane & 16) ? s4[i] : s4[2 + i], keep = (lane & 16) ? s4[2 + i] : s4[i]; s2[i] = keep + __shfl_xor(send, 16); }
;                 { const float send = (lane & 8) ? s2[0] : s2[1], keep = (lane & 8) ? s2[1] : s2[0]; s1 = keep + __shfl_xor(send, 8); }
;                 s1 += __shfl_xor(s1, 4); s1 += __shfl_xor(s1, 2); s1 += __shfl_xor(s1, 1);
	v_add_f32_dpp v160, v160, v160 quad_perm:[1,0,3,2] row_mask:0xf bank_mask:0xf
	v_add_f32_e32 v189, v189, v206
	v_add_f32_e32 v189, v207, v189
	v_mul_f32_e32 v206, v201, v65
	v_mul_f32_e32 v207, v163, v67
	s_waitcnt lgkmcnt(0)
	v_add_f32_dpp v160, v160, v160 quad_perm:[2,3,0,1] row_mask:0xf bank_mask:0xf
	v_fmac_f32_e32 v206, v200, v64
	v_fmac_f32_e32 v207, v162, v66
	v_add_f32_e32 v206, v206, v207
	v_add_f32_e32 v202, v202, v206
	s_waitcnt lgkmcnt(0)
	v_add_f32_dpp v160, v160, v160 row_half_mirror row_mask:0xf bank_mask:0xf
	v_mul_f32_e32 v206, v201, v49
	v_mul_f32_e32 v207, v163, v51
	v_fmac_f32_e32 v206, v200, v48
	v_fmac_f32_e32 v207, v162, v50
	s_waitcnt lgkmcnt(0)
	v_add_f32_dpp v160, v160, v160 row_mirror row_mask:0xf bank_mask:0xf
	v_mov_b32_e32 v188, v160
	s_nop 1
	v_permlane16_swap_b32_e32 v160, v188
	v_add_f32_e32 v206, v206, v207
	v_add_f32_e32 v203, v203, v206
	v_mul_f32_e32 v206, v201, v33
	v_mul_f32_e32 v207, v163, v35
	s_waitcnt lgkmcnt(0)
	v_add_f32_e32 v160, v160, v188
	v_mov_b32_e32 v188, v160
	s_nop 1
	v_permlane32_swap_b32_e32 v160, v188
	v_fmac_f32_e32 v206, v200, v32
	v_fmac_f32_e32 v207, v162, v34
	v_add_f32_e32 v206, v206, v207
	v_add_f32_e32 v204, v204, v206
	s_waitcnt lgkmcnt(0)
	v_add_f32_e32 v160, v160, v188
	v_fmamk_f32 v160, v160, 0x3a800000, v177
	v_mul_f32_e32 v188, 0x4f800000, v160
	v_cmp_gt_f32_e32 vcc, s3, v160
	v_mul_f32_e32 v206, v201, v17
	v_mul_f32_e32 v207, v163, v19
	v_cndmask_b32_e32 v160, v160, v188, vcc
	v_sqrt_f32_e32 v188, v160
	v_fmac_f32_e32 v206, v200, v16
	v_fmac_f32_e32 v207, v162, v18
	v_add_f32_e32 v206, v206, v207
	v_add_u32_e32 v208, -1, v188
	v_fma_f32 v209, -v208, v188, v160
	v_cmp_ge_f32_e64 s[12:13], 0, v209
	v_add_u32_e32 v209, 1, v188
	v_add_f32_e32 v205, v205, v206
	v_cndmask_b32_e64 v208, v188, v208, s[12:13]
	v_fma_f32 v188, -v209, v188, v160
	v_cmp_lt_f32_e64 s[12:13], 0, v188
	s_nop 1
	v_cndmask_b32_e64 v188, v208, v209, s[12:13]
	v_mul_f32_e32 v208, 0x37800000, v188
	v_cndmask_b32_e32 v188, v188, v208, vcc
	v_cmp_class_f32_e32 vcc, v160, v179
	s_nop 1
	v_cndmask_b32_e32 v160, v188, v160, vcc
	v_div_scale_f32 v188, s[12:13], v160, v160, 1.0
	v_rcp_f32_e32 v208, v188
	s_nop 0
	v_fma_f32 v206, -v188, v208, 1.0
	v_fmac_f32_e32 v208, v206, v208
	v_div_scale_f32 v206, vcc, 1.0, v160, 1.0
	v_mul_f32_e32 v207, v206, v208
	v_fma_f32 v209, -v188, v207, v206
	v_fmac_f32_e32 v207, v209, v208
	v_fma_f32 v188, -v188, v207, v206
	v_div_fmas_f32 v188, v188, v208, v207
	v_div_fixup_f32 v160, v188, v160, 1.0
	v_cndmask_b32_e64 v188, v161, v202, s[4:5]
	ds_bpermute_b32 v188, v196, v188
	v_pk_mul_f32 v[174:175], v[160:161], v[174:175] op_sel_hi:[0,1]
	v_pk_mul_f32 v[172:173], v[160:161], v[172:173] op_sel_hi:[0,1]
	v_cvt_pk_bf16_f32 v172, v172, v173
	v_cvt_pk_bf16_f32 v173, v174, v175
	v_cndmask_b32_e64 v174, v187, v203, s[4:5]
	v_cndmask_b32_e64 v161, v202, v161, s[4:5]
	v_cndmask_b32_e64 v175, v203, v187, s[4:5]
	ds_bpermute_b32 v174, v196, v174
	v_cndmask_b32_e64 v187, v199, v204, s[4:5]
	s_waitcnt lgkmcnt(1)
	v_add_f32_e32 v161, v161, v188
	ds_bpermute_b32 v187, v196, v187
	v_cndmask_b32_e64 v188, v189, v205, s[4:5]
	ds_bpermute_b32 v188, v196, v188
	s_waitcnt lgkmcnt(2)
	v_add_f32_e32 v174, v175, v174
	v_cndmask_b32_e64 v175, v204, v199, s[4:5]
	s_waitcnt lgkmcnt(1)
	v_add_f32_e32 v175, v175, v187
	v_cndmask_b32_e64 v187, v205, v189, s[4:5]
	s_waitcnt lgkmcnt(0)
	v_add_f32_e32 v187, v187, v188
	v_cndmask_b32_e64 v188, v161, v175, s[6:7]
	v_cndmask_b32_e64 v189, v174, v187, s[6:7]
	ds_bpermute_b32 v188, v195, v188
	ds_bpermute_b32 v189, v195, v189
	global_store_dwordx2 v[182:183], v[172:173], off
	v_cndmask_b32_e64 v161, v175, v161, s[6:7]
	v_cndmask_b32_e64 v172, v187, v174, s[6:7]
	s_waitcnt lgkmcnt(0)
	v_add_f32_e32 v161, v161, v188
	v_add_f32_e32 v172, v172, v189
	v_cndmask_b32_e64 v173, v161, v172, s[8:9]
	ds_bpermute_b32 v173, v194, v173
	v_pk_mul_f32 v[170:171], v[160:161], v[170:171] op_sel_hi:[0,1]
	v_pk_mul_f32 v[168:169], v[160:161], v[168:169] op_sel_hi:[0,1]
	v_cndmask_b32_e64 v161, v172, v161, s[8:9]
	v_cvt_pk_bf16_f32 v168, v168, v169
	s_waitcnt lgkmcnt(0)
	v_add_f32_e32 v161, v161, v173
	ds_bpermute_b32 v172, v193, v161
	v_pk_mul_f32 v[166:167], v[160:161], v[166:167] op_sel_hi:[0,1]
	v_pk_mul_f32 v[164:165], v[160:161], v[164:165] op_sel_hi:[0,1]
	v_cvt_pk_bf16_f32 v169, v170, v171
	global_store_dwordx2 v[182:183], v[168:169], off offset:512
	s_waitcnt lgkmcnt(0)
	v_add_f32_e32 v161, v161, v172
	ds_bpermute_b32 v168, v192, v161
	v_cvt_pk_bf16_f32 v164, v164, v165
	v_cvt_pk_bf16_f32 v165, v166, v167
	global_store_dwordx2 v[182:183], v[164:165], off offset:1024
	v_pk_mul_f32 v[164:165], v[160:161], v[162:163] op_sel_hi:[0,1]
	s_waitcnt lgkmcnt(0)
	v_add_f32_e32 v161, v161, v168
	ds_bpermute_b32 v162, v191, v161
	v_pk_mul_f32 v[166:167], v[160:161], v[200:201] op_sel_hi:[0,1]
	v_cvt_pk_bf16_f32 v166, v166, v167
	v_cvt_pk_bf16_f32 v167, v164, v165
	global_store_dwordx2 v[182:183], v[166:167], off offset:1536
	s_and_saveexec_b64 s[12:13], s[10:11]
	s_cbranch_execz .LBB0_36
; __global__ void __launch_bounds__(NWAVES * 64, 2) mk_fwd(Args args) {
;     ...
;                 if ((lane & 7) == 0) { const float zz = s1 * rs + bfl; LOGF[(size_t)m * 8 + hsel] = fminf(zz, 0.f) - log1pf(expf(-fabsf(zz))); }
	s_waitcnt lgkmcnt(0)
	v_add_f32_e32 v161, v161, v162
	v_fma_f32 v160, v160, v161, v190
	v_mul_f32_e64 v161, |v160|, s15
	v_fma_f32 v162, |v160|, s15, -v161
	v_rndne_f32_e32 v163, v161
	v_fma_f32 v162, |v160|, s33, v162
	v_sub_f32_e32 v161, v161, v163
	v_add_f32_e32 v161, v161, v162
	v_exp_f32_e32 v161, v161
	v_cvt_i32_f32_e32 v162, v163
	v_cmp_ngt_f32_e64 vcc, |v160|, s34
	v_min_f32_e32 v174, 0, v160
	v_ldexp_f32 v161, v161, v162
	v_cndmask_b32_e32 v161, 0, v161, vcc
	v_cmp_nlt_f32_e64 vcc, |v160|, s35
	s_nop 1
	v_cndmask_b32_e32 v175, v198, v161, vcc
	v_add_f32_e32 v162, 1.0, v175
	v_add_f32_e32 v160, -1.0, v162
	v_sub_f32_e32 v161, v160, v162
	v_add_f32_e32 v161, 1.0, v161
	v_sub_f32_e32 v160, v175, v160
	v_add_f32_e32 v163, v160, v161
	v_frexp_mant_f32_e32 v164, v162
	v_cvt_f64_f32_e32 v[160:161], v162
	v_frexp_exp_i32_f64_e32 v160, v[160:161]
	v_cmp_gt_f32_e32 vcc, s37, v164
	s_nop 1
	v_subbrev_co_u32_e32 v168, vcc, 0, v160, vcc
	v_sub_u32_e32 v160, 0, v168
	v_ldexp_f32 v161, v162, v160
	v_add_f32_e32 v162, -1.0, v161
	v_add_f32_e32 v164, 1.0, v161
	v_ldexp_f32 v160, v163, v160
	v_add_f32_e32 v163, 1.0, v162
	v_add_f32_e32 v165, -1.0, v164
	v_sub_f32_e32 v163, v161, v163
	v_sub_f32_e32 v161, v161, v165
	v_add_f32_e32 v163, v160, v163
	v_add_f32_e32 v160, v160, v161
	v_add_f32_e32 v169, v164, v160
	v_rcp_f32_e32 v171, v169
	v_sub_f32_e32 v161, v164, v169
	v_add_f32_e32 v170, v160, v161
	v_add_f32_e32 v161, v162, v163
	v_mul_f32_e32 v173, v161, v171
	v_sub_f32_e32 v160, v162, v161
	v_mul_f32_e32 v162, v169, v173
	v_fma_f32 v164, v173, v169, -v162
	v_fmac_f32_e32 v164, v173, v170
	v_add_f32_e32 v172, v163, v160
	v_add_f32_e32 v160, v162, v164
	v_sub_f32_e32 v163, v161, v160
	v_pk_add_f32 v[166:167], v[160:161], v[162:163] neg_lo:[0,1] neg_hi:[0,1]
	v_mov_b32_e32 v165, v160
	v_pk_add_f32 v[160:161], v[166:167], v[164:165] neg_lo:[0,1] neg_hi:[0,1]
	v_cmp_neq_f32_e32 vcc, s36, v175
	v_add_f32_e32 v161, v172, v161
	v_add_f32_e32 v160, v160, v161
	v_add_f32_e32 v161, v163, v160
	v_mul_f32_e32 v172, v171, v161
	v_mul_f32_e32 v162, v169, v172
	v_fma_f32 v164, v172, v169, -v162
	v_fmac_f32_e32 v164, v172, v170
	v_sub_f32_e32 v163, v163, v161
	v_add_f32_e32 v169, v160, v163
	v_add_f32_e32 v160, v162, v164
	v_sub_f32_e32 v163, v161, v160
	v_pk_add_f32 v[166:167], v[160:161], v[162:163] neg_lo:[0,1] neg_hi:[0,1]
	v_mov_b32_e32 v165, v160
	v_pk_add_f32 v[160:161], v[166:167], v[164:165] neg_lo:[0,1] neg_hi:[0,1]
	s_nop 0
	v_add_f32_e32 v161, v169, v161
	v_add_f32_e32 v160, v160, v161
	v_add_f32_e32 v161, v173, v172
	v_add_f32_e32 v160, v163, v160
	v_sub_f32_e32 v162, v161, v173
	v_mul_f32_e32 v160, v171, v160
	v_sub_f32_e32 v162, v172, v162
	v_add_f32_e32 v162, v162, v160
	v_add_f32_e32 v164, v161, v162
	v_mul_f32_e32 v165, v164, v164
	v_fmamk_f32 v160, v165, 0x3e9b6dac, v197
	v_fmaak_f32 v187, v165, v160, 0x3f2aaada
	v_cvt_f32_i32_e32 v160, v168
	v_sub_f32_e32 v161, v164, v161
	v_sub_f32_e32 v161, v162, v161
	v_ldexp_f32 v166, v161, 1
	v_mul_f32_e32 v161, v164, v165
	v_ldexp_f32 v163, v164, 1
	v_pk_mul_f32 v[164:165], v[160:161], v[186:187]
	s_nop 0
	v_fma_f32 v162, v160, s39, -v164
	v_fmac_f32_e32 v162, 0xb102e308, v160
	v_pk_add_f32 v[160:161], v[164:165], v[162:163]
	s_nop 0
	v_sub_f32_e32 v163, v161, v163
	v_sub_f32_e32 v163, v165, v163
	v_add_f32_e32 v167, v166, v163
	v_mov_b32_e32 v166, v164
	v_pk_add_f32 v[164:165], v[160:161], v[164:165] neg_lo:[0,1] neg_hi:[0,1]
	v_pk_add_f32 v[168:169], v[160:161], v[166:167]
	v_mov_b32_e32 v163, v160
	v_mov_b32_e32 v165, v169
	v_pk_add_f32 v[170:171], v[162:163], v[164:165] neg_lo:[0,1] neg_hi:[0,1]
	v_pk_add_f32 v[162:163], v[162:163], v[164:165]
	v_mov_b32_e32 v166, v167
	v_pk_add_f32 v[164:165], v[162:163], v[160:161] op_sel:[1,0] op_sel_hi:[0,1] neg_lo:[0,1] neg_hi:[0,1]
	v_pk_add_f32 v[172:173], v[168:169], v[164:165] op_sel_hi:[1,0] neg_lo:[0,1] neg_hi:[0,1]
	v_mov_b32_e32 v168, v169
	v_mov_b32_e32 v169, v163
	v_pk_mov_b32 v[164:165], v[160:161], v[164:165] op_sel:[1,0]
	v_mov_b32_e32 v167, v160
	v_pk_add_f32 v[164:165], v[168:169], v[164:165] neg_lo:[0,1] neg_hi:[0,1]
	v_mov_b32_e32 v172, v170
	v_pk_add_f32 v[160:161], v[166:167], v[164:165] neg_lo:[0,1] neg_hi:[0,1]
	v_mov_b32_e32 v171, v163
	v_pk_add_f32 v[164:165], v[172:173], v[160:161]
	s_nop 0
	v_pk_add_f32 v[166:167], v[164:165], v[164:165] op_sel:[0,1] op_sel_hi:[1,0]
	s_nop 0
	v_pk_add_f32 v[162:163], v[162:163], v[166:167] op_sel:[1,0] op_sel_hi:[0,1]
	v_mov_b32_e32 v165, v162
	v_pk_add_f32 v[168:169], v[164:165], v[170:171] neg_lo:[0,1] neg_hi:[0,1]
	v_mov_b32_e32 v161, v166
	v_sub_f32_e32 v163, v164, v168
	v_pk_add_f32 v[160:161], v[160:161], v[168:169] neg_lo:[0,1] neg_hi:[0,1]
	v_sub_f32_e32 v163, v170, v163
	v_add_f32_e32 v160, v160, v163
	v_add_f32_e32 v160, v160, v161
	v_add_f32_e32 v160, v162, v160
	v_cndmask_b32_e32 v160, v198, v160, vcc
	v_cmp_lt_f32_e64 vcc, |v175|, s42
	s_nop 1
	v_cndmask_b32_e32 v160, v160, v175, vcc
	v_sub_f32_e32 v160, v174, v160
	global_store_dword v[180:181], v160, off
	s_branch .LBB0_36
